# pooling item: 64x64 weight matrix fetched by coalesced LDS-DMA and read as MFMA fragments from LDS instead of eight row-strided fragment loads per lane
# baseline (speedup 1.0000x reference)
; DI void pool_item(const Params& p, int l, int token0, char* lds) {
;     ...
;   {
;     const int g_ = w & 3, tok_ = token0 + (w >> 2) * 32 + r;
; #pragma unroll
;     for (int mo = 0; mo < 2; ++mo)
; #pragma unroll
;       for (int gg = 0; gg < 4; ++gg) {
;         const int oc = mo * 32 + 8 * gg + 4 * h;
;         scp[mo][gg] = *(const f32x4*)(p.pool_scale + l * 256 + g_ * 64 + oc);
;         gvp[mo][gg] = *(const u32x2*)(p.P + (size_t)tok_ * INW + 1536 + g_ * 64 + oc);
;       }
;   }
;   for (int e = tid; e < 80 * 32; e += NTHREADS) {
;     const int row = e >> 5, ch = e & 31;
;     const int s = s0 - 8 + row;
;     u32x4 v = {0u, 0u, 0u, 0u};
;     if (s >= 0 && s < L) v = *(const u32x4*)(p.P + (size_t)(seqbase + s) * INW + 1280 + ch * 8);
;     *(u32x4*)(zt + row * 512 + ch * 16) = v;
;   }
;   __syncthreads();
;     ...
;     const bf16_t* wp = p.pwT + (size_t)((l * 4 + g) * 64) * 64;
; #pragma unroll
;     for (int ks = 0; ks < 4; ++ks) {
;       bf16x8 a[2], b[2];
; #pragma unroll
;       for (int mo = 0; mo < 2; ++mo) a[mo] = *(const bf16x8*)(wp + (size_t)(mo * 32 + r) * 64 + ks * 16 + h * 8);
.LBB0_83:
	v_readlane_b32 s0, v255, 17
	s_cmp_lt_i32 s83, s0
	s_mov_b64 s[2:3], -1
	s_cbranch_scc1 .LBB0_97
	v_readlane_b32 s0, v255, 17
	v_readlane_b32 s14, v254, 49
	v_readlane_b32 s15, v254, 50
	v_readlane_b32 s16, v254, 55
	v_readlane_b32 s17, v254, 56
	v_readlane_b32 s18, v254, 45
	v_readlane_b32 s19, v254, 46
	v_readlane_b32 s20, v255, 15
	v_readlane_b32 s21, v255, 16
	v_readlane_b32 s22, v255, 12
	s_nop 3
	s_sub_i32 s0, s83, s0
	s_lshl_b32 s4, s0, 6
	s_cmp_lt_u32 s4, 0x8000
	s_movk_i32 s2, 0x100
	s_cselect_b32 s5, 0x800, s2
	s_movk_i32 s2, 0xff
	s_cselect_b32 s2, 0x7ff, s2
	s_and_b32 s6, s4, s2
	s_sub_i32 s2, s4, 8
	s_ashr_i32 s3, s2, 31
	s_mul_i32 s7, s2, 0x1600
	s_mul_hi_i32 s23, s2, 0x1600
	s_add_u32 s24, s14, s7
	s_addc_u32 s25, s15, s23
	s_add_u32 s24, s24, 0xa00
	s_addc_u32 s25, s25, 0
	s_mul_i32 s7, s4, 0x1600
	s_mul_hi_u32 s23, s4, 0x1600
	s_add_u32 s26, s14, s7
	s_addc_u32 s27, s15, s23
	s_add_u32 s26, s26, 0xc00
	s_addc_u32 s27, s27, 0
	s_lshl_b32 s7, s4, 11
	s_add_u32 s16, s16, s7
	s_addc_u32 s17, s17, 0
	s_add_u32 s16, s16, 0x400
	s_addc_u32 s17, s17, 0
	v_lshrrev_b32_e32 v134, 5, v251
	v_and_b32_e32 v135, 31, v251
	v_mul_u32_u24_e32 v136, 0x1600, v134
	v_lshl_add_u32 v136, v135, 4, v136
	s_sub_i32 s2, s6, 8
	v_mov_b32_e32 v0, v134
	v_add_u32_e32 v0, s2, v0
	v_cmp_gt_u32_e32 vcc, s5, v0
	v_mov_b32_e32 v2, 0
	v_mov_b32_e32 v3, 0
	v_mov_b32_e32 v4, 0
	v_mov_b32_e32 v5, 0
	s_and_saveexec_b64 s[8:9], vcc
	global_load_dwordx4 v[2:5], v136, s[24:25]
	s_mov_b64 exec, s[8:9]
	v_add_u32_e32 v0, 16, v134
	v_add_u32_e32 v0, s2, v0
	v_cmp_gt_u32_e32 vcc, s5, v0
	v_mov_b32_e32 v6, 0
	v_mov_b32_e32 v7, 0
	v_mov_b32_e32 v8, 0
	v_mov_b32_e32 v9, 0
	s_and_saveexec_b64 s[8:9], vcc
	v_add_u32_e32 v137, 0x16000, v136
	global_load_dwordx4 v[6:9], v137, s[24:25]
	s_mov_b64 exec, s[8:9]
	v_add_u32_e32 v0, 32, v134
	v_add_u32_e32 v0, s2, v0
	v_cmp_gt_u32_e32 vcc, s5, v0
	v_mov_b32_e32 v10, 0
	v_mov_b32_e32 v11, 0
	v_mov_b32_e32 v12, 0
	v_mov_b32_e32 v13, 0
	s_and_saveexec_b64 s[8:9], vcc
	v_add_u32_e32 v137, 0x2c000, v136
	global_load_dwordx4 v[10:13], v137, s[24:25]
	s_mov_b64 exec, s[8:9]
	v_add_u32_e32 v0, 48, v134
	v_add_u32_e32 v0, s2, v0
	v_cmp_gt_u32_e32 vcc, s5, v0
	v_mov_b32_e32 v14, 0
	v_mov_b32_e32 v15, 0
	v_mov_b32_e32 v16, 0
	v_mov_b32_e32 v17, 0
	s_and_saveexec_b64 s[8:9], vcc
	v_add_u32_e32 v137, 0x42000, v136
	global_load_dwordx4 v[14:17], v137, s[24:25]
	s_mov_b64 exec, s[8:9]
	v_add_u32_e32 v0, 64, v134
	v_add_u32_e32 v0, s2, v0
	v_cmp_gt_u32_e32 vcc, s5, v0
	v_mov_b32_e32 v18, 0
	v_mov_b32_e32 v19, 0
	v_mov_b32_e32 v20, 0
	v_mov_b32_e32 v21, 0
	s_and_saveexec_b64 s[8:9], vcc
	v_add_u32_e32 v137, 0x58000, v136
	global_load_dwordx4 v[18:21], v137, s[24:25]
	s_mov_b64 exec, s[8:9]
	v_mov_b32_e32 v0, v134
	v_xor_b32_e32 v138, v135, v0
	v_and_b32_e32 v139, 31, v0
	v_xor_b32_e32 v138, v135, v139
	v_mul_u32_u24_e32 v139, 0x1600, v0
	v_lshl_add_u32 v139, v138, 4, v139
	global_load_dwordx4 v[22:25], v139, s[26:27]
	v_add_u32_e32 v0, 16, v134
	v_xor_b32_e32 v138, v135, v0
	v_and_b32_e32 v139, 31, v0
	v_xor_b32_e32 v138, v135, v139
	v_mul_u32_u24_e32 v139, 0x1600, v0
	v_lshl_add_u32 v139, v138, 4, v139
	global_load_dwordx4 v[26:29], v139, s[26:27]
	v_add_u32_e32 v0, 32, v134
	v_xor_b32_e32 v138, v135, v0
	v_and_b32_e32 v139, 31, v0
	v_xor_b32_e32 v138, v135, v139
	v_mul_u32_u24_e32 v139, 0x1600, v0
	v_lshl_add_u32 v139, v138, 4, v139
	global_load_dwordx4 v[30:33], v139, s[26:27]
	v_add_u32_e32 v0, 48, v134
	v_xor_b32_e32 v138, v135, v0
	v_and_b32_e32 v139, 31, v0
	v_xor_b32_e32 v138, v135, v139
	v_mul_u32_u24_e32 v139, 0x1600, v0
	v_lshl_add_u32 v139, v138, 4, v139
	global_load_dwordx4 v[34:37], v139, s[26:27]
	v_lshrrev_b32_e32 v140, 6, v251
	s_nop 0
	v_readfirstlane_b32 s28, v140
	s_nop 3
	s_and_b32 s29, s28, 3
	s_add_i32 s2, s22, s29
	s_lshl_b32 s2, s2, 13
	s_add_u32 s18, s18, s2
	s_addc_u32 s19, s19, 0
	s_lshl_b32 s2, s29, 8
	s_add_u32 s20, s20, s2
	s_addc_u32 s21, s21, 0
	v_and_b32_e32 v141, 31, v251
	v_bfe_u32 v142, v251, 5, 1
	v_lshlrev_b32_e32 v143, 7, v141
	v_lshl_or_b32 v143, v142, 4, v143
	v_add_u32_e32 v159, 0x1000, v143
	s_lshr_b32 s10, s28, 2
	s_lshl_b32 s11, s10, 12
	s_add_u32 s18, s18, s11
	s_addc_u32 s19, s19, 0
	s_lshl_b32 s12, s29, 13
	s_add_u32 s12, s12, 0x1a000
	s_cmp_eq_u32 s29, 3
	s_cselect_b32 s12, 0x21e40, s12
	s_add_u32 m0, s12, s11
	v_lshrrev_b32_e32 v159, 3, v240
	v_and_b32_e32 v143, 7, v240
	v_lshrrev_b32_e32 v0, 1, v159
	v_xor_b32_e32 v143, v143, v0
	v_lshlrev_b32_e32 v159, 7, v159
	v_lshl_or_b32 v143, v143, 4, v159
	v_xor_b32_e32 v159, 0x40, v143
	global_load_lds_dwordx4 v143, s[18:19]
	global_load_lds_dwordx4 v159, s[18:19] offset:1024
	global_load_lds_dwordx4 v143, s[18:19] offset:2048
	global_load_lds_dwordx4 v159, s[18:19] offset:3072
	v_lshlrev_b32_e32 v144, 4, v142
	global_load_dwordx4 v[70:73], v144, s[20:21] offset:0
	global_load_dwordx4 v[74:77], v144, s[20:21] offset:32
	global_load_dwordx4 v[78:81], v144, s[20:21] offset:64
	global_load_dwordx4 v[82:85], v144, s[20:21] offset:96
	global_load_dwordx4 v[86:89], v144, s[20:21] offset:128
	global_load_dwordx4 v[90:93], v144, s[20:21] offset:160
	global_load_dwordx4 v[94:97], v144, s[20:21] offset:192
	global_load_dwordx4 v[98:101], v144, s[20:21] offset:224
	v_lshlrev_b32_e32 v145, 9, v134
	v_and_b32_e32 v146, 1, v134
	v_lshlrev_b32_e32 v146, 3, v146
	v_xor_b32_e32 v146, v146, v135
	v_lshl_or_b32 v145, v146, 4, v145
	s_waitcnt vmcnt(16)
	ds_write_b128 v145, v[2:5]
	ds_write_b128 v145, v[6:9] offset:8192
	ds_write_b128 v145, v[10:13] offset:16384
	ds_write_b128 v145, v[14:17] offset:24576
	ds_write_b128 v145, v[18:21] offset:32768
	v_lshlrev_b32_e32 v147, 9, v134
	v_lshl_or_b32 v147, v135, 4, v147
	v_add_u32_e32 v147, 0x12000, v147
	s_waitcnt vmcnt(12)
	ds_write_b128 v147, v[22:25]
	ds_write_b128 v147, v[26:29] offset:8192
	ds_write_b128 v147, v[30:33] offset:16384
	ds_write_b128 v147, v[34:37] offset:24576
	s_waitcnt vmcnt(8)
	s_waitcnt lgkmcnt(0)
	s_barrier
	v_and_b32_e32 v148, 63, v251
	s_cmp_lt_u32 s28, 4
	s_cbranch_scc1 .Lpl_g3
	s_cmp_lt_u32 s28, 6
	s_cbranch_scc1 .Lpl_g2
	s_cmp_eq_u32 s28, 6
	s_cbranch_scc1 .Lpl_g1

; DI f32x16 mfma32(bf16x8 a, bf16x8 b, f32x16 c) { return __builtin_amdgcn_mfma_f32_32x32x16_bf16(a, b, c, 0, 0, 0); }
; DI void pool_item(const Params& p, int l, int token0, char* lds) {
;     ...
;   {
;     const int g = w & 3, tn0 = w >> 2;
;     f32x16 acc[2][2];
; #pragma unroll
;     for (int a = 0; a < 2; ++a)
; #pragma unroll
;       for (int b = 0; b < 2; ++b) acc[a][b] = zero16();
;     const bf16_t* wp = p.pwT + (size_t)((l * 4 + g) * 64) * 64;
; #pragma unroll
;     for (int ks = 0; ks < 4; ++ks) {
;       bf16x8 a[2], b[2];
; #pragma unroll
;       for (int mo = 0; mo < 2; ++mo) a[mo] = *(const bf16x8*)(wp + (size_t)(mo * 32 + r) * 64 + ks * 16 + h * 8);
;       {
;         const int row = tn0 * 32 + r;
;         const int ch = g * 8 + 2 * ks + h;
;         b[0] = *(const bf16x8*)(pl + row * 512 + ((ch ^ (row & 15)) << 4));
;       }
; #pragma unroll
;       for (int mo = 0; mo < 2; ++mo) acc[mo][0] = mfma32(a[mo], b[0], acc[mo][0]);
;     }
;     ...
;           const int oc = mo * 32 + 8 * gg + 4 * h;
;           const f32x4 sc = scp[mo][gg];
;           const u32x2 gv = gvp[mo][gg];
.Lpl_done:
	s_waitcnt lgkmcnt(0)
	s_barrier
	s_lshr_b32 s2, s28, 2
	v_mov_b32_e32 v150, s2
	v_lshl_or_b32 v150, v150, 5, v141
	v_lshlrev_b32_e32 v151, 9, v150
	v_and_b32_e32 v152, 15, v150
	v_mov_b32_e32 v102, 0
	v_mov_b32_e32 v103, 0
	v_mov_b32_e32 v104, 0
	v_mov_b32_e32 v105, 0
	v_mov_b32_e32 v106, 0
	v_mov_b32_e32 v107, 0
	v_mov_b32_e32 v108, 0
	v_mov_b32_e32 v109, 0
	v_mov_b32_e32 v110, 0
	v_mov_b32_e32 v111, 0
	v_mov_b32_e32 v112, 0
	v_mov_b32_e32 v113, 0
	v_mov_b32_e32 v114, 0
	v_mov_b32_e32 v115, 0
	v_mov_b32_e32 v116, 0
	v_mov_b32_e32 v117, 0
	v_mov_b32_e32 v118, 0
	v_mov_b32_e32 v119, 0
	v_mov_b32_e32 v120, 0
	v_mov_b32_e32 v121, 0
	v_mov_b32_e32 v122, 0
	v_mov_b32_e32 v123, 0
	v_mov_b32_e32 v124, 0
	v_mov_b32_e32 v125, 0
	v_mov_b32_e32 v126, 0
	v_mov_b32_e32 v127, 0
	v_mov_b32_e32 v128, 0
	v_mov_b32_e32 v129, 0
	v_mov_b32_e32 v130, 0
	v_mov_b32_e32 v131, 0
	v_mov_b32_e32 v132, 0
	v_mov_b32_e32 v133, 0
	v_lshrrev_b32_e32 v143, 1, v141
	v_and_b32_e32 v143, 7, v143
	v_xor_b32_e32 v143, v143, v142
	v_lshlrev_b32_e32 v159, 7, v141
	v_add_u32_e32 v159, s12, v159
	v_lshl_add_u32 v153, v143, 4, v159
	ds_read_b128 v[38:41], v153
	ds_read_b128 v[42:45], v153 offset:4096
	v_xor_b32_e32 v153, 2, v143
	v_lshl_add_u32 v153, v153, 4, v159
	ds_read_b128 v[46:49], v153
	ds_read_b128 v[50:53], v153 offset:4096
	v_xor_b32_e32 v153, 4, v143
	v_lshl_add_u32 v153, v153, 4, v159
	ds_read_b128 v[54:57], v153
	ds_read_b128 v[58:61], v153 offset:4096
	v_xor_b32_e32 v153, 6, v143
	v_lshl_add_u32 v153, v153, 4, v159
	ds_read_b128 v[62:65], v153
	ds_read_b128 v[66:69], v153 offset:4096
	v_mov_b32_e32 v153, s29
	v_lshl_add_u32 v153, v153, 3, v142
	v_add_u32_e32 v153, 0, v153
	v_xor_b32_e32 v153, v153, v152
	v_lshl_or_b32 v153, v153, 4, v151
	ds_read_b128 v[160:163], v153 offset:40960
	v_mov_b32_e32 v153, s29
	v_lshl_add_u32 v153, v153, 3, v142
	v_add_u32_e32 v153, 2, v153
	v_xor_b32_e32 v153, v153, v152
	v_lshl_or_b32 v153, v153, 4, v151
	ds_read_b128 v[164:167], v153 offset:40960
	v_mov_b32_e32 v153, s29
	v_lshl_add_u32 v153, v153, 3, v142
	v_add_u32_e32 v153, 4, v153
	v_xor_b32_e32 v153, v153, v152
	v_lshl_or_b32 v153, v153, 4, v151
	ds_read_b128 v[168:171], v153 offset:40960
	v_mov_b32_e32 v153, s29
	v_lshl_add_u32 v153, v153, 3, v142
	v_add_u32_e32 v153, 6, v153
	v_xor_b32_e32 v153, v153, v152
	v_lshl_or_b32 v153, v153, 4, v151
	ds_read_b128 v[172:175], v153 offset:40960
	s_waitcnt vmcnt(8)
	s_waitcnt lgkmcnt(3)
	v_mfma_f32_32x32x16_bf16 v[102:117], v[38:41], v[160:163], v[102:117]
	v_mfma_f32_32x32x16_bf16 v[118:133], v[42:45], v[160:163], v[118:133]
	s_waitcnt lgkmcnt(2)
	v_mfma_f32_32x32x16_bf16 v[102:117], v[46:49], v[164:167], v[102:117]
	v_mfma_f32_32x32x16_bf16 v[118:133], v[50:53], v[164:167], v[118:133]
	s_waitcnt lgkmcnt(1)
	v_mfma_f32_32x32x16_bf16 v[102:117], v[54:57], v[168:171], v[102:117]
	v_mfma_f32_32x32x16_bf16 v[118:133], v[58:61], v[168:171], v[118:133]
	s_waitcnt lgkmcnt(0)
	v_mfma_f32_32x32x16_bf16 v[102:117], v[62:65], v[172:175], v[102:117]
	v_mfma_f32_32x32x16_bf16 v[118:133], v[66:69], v[172:175], v[118:133]
	v_and_b32_e32 v154, 31, v150
	v_lshlrev_b32_e32 v155, 3, v142
	v_or_b32_e32 v155, v155, v151
	v_add_u32_e32 v155, 0x12000, v155
	v_mov_b32_e32 v153, s29
	v_lshlrev_b32_e32 v153, 3, v153
	v_or_b32_e32 v153, 0, v153
	v_xor_b32_e32 v153, v153, v154
	v_lshl_or_b32 v192, v153, 4, v155
	ds_read_b64 v[208:209], v192
	v_mov_b32_e32 v153, s29
	v_lshlrev_b32_e32 v153, 3, v153
	v_or_b32_e32 v153, 1, v153
	v_xor_b32_e32 v153, v153, v154
	v_lshl_or_b32 v193, v153, 4, v155
	ds_read_b64 v[210:211], v193
	v_mov_b32_e32 v153, s29
	v_lshlrev_b32_e32 v153, 3, v153
	v_or_b32_e32 v153, 2, v153
	v_xor_b32_e32 v153, v153, v154
	v_lshl_or_b32 v194, v153, 4, v155
	ds_read_b64 v[212:213], v194
	v_mov_b32_e32 v153, s29
	v_lshlrev_b32_e32 v153, 3, v153
	v_or_b32_e32 v153, 3, v153
	v_xor_b32_e32 v153, v153, v154
	v_lshl_or_b32 v195, v153, 4, v155
	ds_read_b64 v[214:215], v195
	v_mov_b32_e32 v153, s29
	v_lshlrev_b32_e32 v153, 3, v153
	v_or_b32_e32 v153, 4, v153
	v_xor_b32_e32 v153, v153, v154
	v_lshl_or_b32 v196, v153, 4, v155
	ds_read_b64 v[216:217], v196
	v_mov_b32_e32 v153, s29
	v_lshlrev_b32_e32 v153, 3, v153
	v_or_b32_e32 v153, 5, v153
	v_xor_b32_e32 v153, v153, v154
	v_lshl_or_b32 v197, v153, 4, v155
	ds_read_b64 v[218:219], v197
	v_mov_b32_e32 v153, s29
	v_lshlrev_b32_e32 v153, 3, v153
	v_or_b32_e32 v153, 6, v153
	v_xor_b32_e32 v153, v153, v154
	v_lshl_or_b32 v198, v153, 4, v155
	ds_read_b64 v[220:221], v198
	v_mov_b32_e32 v153, s29
	v_lshlrev_b32_e32 v153, 3, v153
	v_or_b32_e32 v153, 7, v153
	v_xor_b32_e32 v153, v153, v154
	v_lshl_or_b32 v199, v153, 4, v155
	ds_read_b64 v[222:223], v199
	s_waitcnt vmcnt(0)
	s_nop 7
	s_nop 3
	s_waitcnt lgkmcnt(7)
; DI float bflo(unsigned u) { return __uint_as_float(u << 16); }
; DI float bfhi(unsigned u) { return __uint_as_float(u & 0xffff0000u); }
; DI void pool_item(const Params& p, int l, int token0, char* lds) {
;     ...
;     {
;       const int tn = 0;
;       const int token = token0 + tn0 * 32 + r;
; #pragma unroll
;       for (int mo = 0; mo < 2; ++mo)
; #pragma unroll
;         for (int gg = 0; gg < 4; ++gg) {
;           const int oc = mo * 32 + 8 * gg + 4 * h;
;           const f32x4 sc = scp[mo][gg];
;           const u32x2 gv = gvp[mo][gg];
;           u32x2 ov;
;           ov[0] = pk2(acc[mo][tn][4 * gg + 0] * sc[0] * bflo(gv[0]), acc[mo][tn][4 * gg + 1] * sc[1] * bfhi(gv[0]));
;           ov[1] = pk2(acc[mo][tn][4 * gg + 2] * sc[2] * bflo(gv[1]), acc[mo][tn][4 * gg + 3] * sc[3] * bfhi(gv[1]));
;           *(u32x2*)(p.Y + (size_t)token * DM + 512 + g * 64 + oc) = ov;
;         }
;     }
;   }
;   __syncthreads();
	v_pk_mul_f32 v[102:103], v[102:103], v[70:71]
	v_pk_mul_f32 v[104:105], v[104:105], v[72:73]
	v_lshlrev_b32_e32 v226, 16, v208
	v_and_b32_e32 v227, 0xffff0000, v208
	v_pk_mul_f32 v[102:103], v[102:103], v[226:227]
	v_lshlrev_b32_e32 v226, 16, v209
	v_and_b32_e32 v227, 0xffff0000, v209
	v_pk_mul_f32 v[104:105], v[104:105], v[226:227]
	v_cvt_pk_bf16_f32 v208, v102, v103
	v_cvt_pk_bf16_f32 v209, v104, v105
	ds_write_b64 v192, v[208:209]
	s_waitcnt lgkmcnt(6)
	v_pk_mul_f32 v[106:107], v[106:107], v[74:75]
	v_pk_mul_f32 v[108:109], v[108:109], v[76:77]
	v_lshlrev_b32_e32 v226, 16, v210
	v_and_b32_e32 v227, 0xffff0000, v210
	v_pk_mul_f32 v[106:107], v[106:107], v[226:227]
	v_lshlrev_b32_e32 v226, 16, v211
	v_and_b32_e32 v227, 0xffff0000, v211
	v_pk_mul_f32 v[108:109], v[108:109], v[226:227]
	v_cvt_pk_bf16_f32 v210, v106, v107
	v_cvt_pk_bf16_f32 v211, v108, v109
	ds_write_b64 v193, v[210:211]
	s_waitcnt lgkmcnt(5)
	v_pk_mul_f32 v[110:111], v[110:111], v[78:79]
	v_pk_mul_f32 v[112:113], v[112:113], v[80:81]
	v_lshlrev_b32_e32 v226, 16, v212
	v_and_b32_e32 v227, 0xffff0000, v212
	v_pk_mul_f32 v[110:111], v[110:111], v[226:227]
	v_lshlrev_b32_e32 v226, 16, v213
	v_and_b32_e32 v227, 0xffff0000, v213
	v_pk_mul_f32 v[112:113], v[112:113], v[226:227]
	v_cvt_pk_bf16_f32 v212, v110, v111
	v_cvt_pk_bf16_f32 v213, v112, v113
	ds_write_b64 v194, v[212:213]
	s_waitcnt lgkmcnt(4)
	v_pk_mul_f32 v[114:115], v[114:115], v[82:83]
	v_pk_mul_f32 v[116:117], v[116:117], v[84:85]
	v_lshlrev_b32_e32 v226, 16, v214
	v_and_b32_e32 v227, 0xffff0000, v214
	v_pk_mul_f32 v[114:115], v[114:115], v[226:227]
	v_lshlrev_b32_e32 v226, 16, v215
	v_and_b32_e32 v227, 0xffff0000, v215
	v_pk_mul_f32 v[116:117], v[116:117], v[226:227]
	v_cvt_pk_bf16_f32 v214, v114, v115
	v_cvt_pk_bf16_f32 v215, v116, v117
	ds_write_b64 v195, v[214:215]
	s_waitcnt lgkmcnt(3)
	v_pk_mul_f32 v[118:119], v[118:119], v[86:87]
	v_pk_mul_f32 v[120:121], v[120:121], v[88:89]
	v_lshlrev_b32_e32 v226, 16, v216
	v_and_b32_e32 v227, 0xffff0000, v216
	v_pk_mul_f32 v[118:119], v[118:119], v[226:227]
	v_lshlrev_b32_e32 v226, 16, v217
	v_and_b32_e32 v227, 0xffff0000, v217
	v_pk_mul_f32 v[120:121], v[120:121], v[226:227]
	v_cvt_pk_bf16_f32 v216, v118, v119
	v_cvt_pk_bf16_f32 v217, v120, v121
	ds_write_b64 v196, v[216:217]
	s_waitcnt lgkmcnt(2)
	v_pk_mul_f32 v[122:123], v[122:123], v[90:91]
	v_pk_mul_f32 v[124:125], v[124:125], v[92:93]
	v_lshlrev_b32_e32 v226, 16, v218
	v_and_b32_e32 v227, 0xffff0000, v218
	v_pk_mul_f32 v[122:123], v[122:123], v[226:227]
	v_lshlrev_b32_e32 v226, 16, v219
	v_and_b32_e32 v227, 0xffff0000, v219
	v_pk_mul_f32 v[124:125], v[124:125], v[226:227]
	v_cvt_pk_bf16_f32 v218, v122, v123
	v_cvt_pk_bf16_f32 v219, v124, v125
	ds_write_b64 v197, v[218:219]
	s_waitcnt lgkmcnt(1)
	v_pk_mul_f32 v[126:127], v[126:127], v[94:95]
	v_pk_mul_f32 v[128:129], v[128:129], v[96:97]
	v_lshlrev_b32_e32 v226, 16, v220
	v_and_b32_e32 v227, 0xffff0000, v220
	v_pk_mul_f32 v[126:127], v[126:127], v[226:227]
	v_lshlrev_b32_e32 v226, 16, v221
	v_and_b32_e32 v227, 0xffff0000, v221
	v_pk_mul_f32 v[128:129], v[128:129], v[226:227]
	v_cvt_pk_bf16_f32 v220, v126, v127
	v_cvt_pk_bf16_f32 v221, v128, v129
	ds_write_b64 v198, v[220:221]
	s_waitcnt lgkmcnt(0)
	v_pk_mul_f32 v[130:131], v[130:131], v[98:99]
	v_pk_mul_f32 v[132:133], v[132:133], v[100:101]
	v_lshlrev_b32_e32 v226, 16, v222
	v_and_b32_e32 v227, 0xffff0000, v222
	v_pk_mul_f32 v[130:131], v[130:131], v[226:227]
	v_lshlrev_b32_e32 v226, 16, v223
	v_and_b32_e32 v227, 0xffff0000, v223
	v_pk_mul_f32 v[132:133], v[132:133], v[226:227]
	v_cvt_pk_bf16_f32 v222, v130, v131
	v_cvt_pk_bf16_f32 v223, v132, v133
	ds_write_b64 v199, v[222:223]
	s_waitcnt lgkmcnt(0)
	s_barrier
	v_lshlrev_b32_e32 v150, 9, v134
	v_lshl_or_b32 v150, v135, 4, v150
	v_add_u32_e32 v150, 0x12000, v150
	ds_read_b128 v[160:163], v150
	ds_read_b128 v[164:167], v150 offset:8192
	ds_read_b128 v[168:171], v150 offset:16384
	ds_read_b128 v[172:175], v150 offset:24576
	v_mov_b32_e32 v0, v134
	v_and_b32_e32 v151, 31, v0
	v_xor_b32_e32 v151, v151, v135
	v_lshlrev_b32_e32 v152, 11, v0
	v_lshl_or_b32 v152, v151, 4, v152
	s_waitcnt lgkmcnt(3)
	global_store_dwordx4 v152, v[160:163], s[16:17]
	v_add_u32_e32 v0, 16, v134
	v_and_b32_e32 v151, 31, v0
	v_xor_b32_e32 v151, v151, v135
	v_lshlrev_b32_e32 v152, 11, v0
	v_lshl_or_b32 v152, v151, 4, v152
	s_waitcnt lgkmcnt(2)
	global_store_dwordx4 v152, v[164:167], s[16:17]
	v_add_u32_e32 v0, 32, v134
	v_and_b32_e32 v151, 31, v0
	v_xor_b32_e32 v151, v151, v135
	v_lshlrev_b32_e32 v152, 11, v0
	v_lshl_or_b32 v152, v151, 4, v152
	s_waitcnt lgkmcnt(1)
	global_store_dwordx4 v152, v[168:171], s[16:17]
	v_add_u32_e32 v0, 48, v134
	v_and_b32_e32 v151, 31, v0
	v_xor_b32_e32 v151, v151, v135
	v_lshlrev_b32_e32 v152, 11, v0
	v_lshl_or_b32 v152, v151, 4, v152
	s_waitcnt lgkmcnt(0)
	global_store_dwordx4 v152, v[172:175], s[16:17]
	s_barrier
	s_mov_b64 s[2:3], 0
	s_branch .LBB0_82
